# GU K-loop: one static s_setprio 1 for the wave half that runs one barrier behind, per-segment priority toggles removed
# baseline (speedup 1.0000x reference)
; #define BAR() { __builtin_amdgcn_sched_barrier(0); __builtin_amdgcn_s_barrier(); asm volatile("" ::: "memory"); __builtin_amdgcn_sched_barrier(0); }
; DI void gemm_stream2(const bf16_t* __restrict__ A, int lda, const bf16_t* __restrict__ Bt, int ldb, int K, int m0, int n0, ...
;     ...
;     const int wave = __builtin_amdgcn_readfirstlane(tid >> 6), lane = tid & 63, wm = wave >> 1, wn = wave & 1, r = lane & 15, q = lane >> 4;
;     const int sc0 = ((lane & 7) ^ (lane >> 4)) * 8, sc1 = ((lane & 7) ^ (4 | (lane >> 4))) * 8;
;     const bf16_t* ga = A + (size_t)(m0 + wave * 32 + (lane >> 3)) * lda;
;     const bf16_t* gb = Bt + (size_t)(n0 + wave * 16 + (lane >> 3)) * ldb;
;     const bf16_t* gan = An + (size_t)(m0n + wave * 32 + (lane >> 3)) * ldan;
;     const bf16_t* gbn = Btn + (size_t)(n0n + wave * 16 + (lane >> 3)) * ldbn;
;     const unsigned wa = (unsigned)wave * 4096u, wbb = 32768u + (unsigned)wave * 2048u;
;     ...
;     const int sw = r >> 1;
;     const unsigned fo0 = (unsigned)(r * 128 + ((q ^ sw) << 4)), fo1 = (unsigned)(r * 128 + (((q ^ sw) ^ 4) << 4));
;     const unsigned aoff = (unsigned)(wm * 64) * 128u, boff = 32768u + (unsigned)(wn * 64) * 128u;
;     const int nk = K / 64;
;     const int grp = wave >> 2;
;     ...
;     int st = rg.st;
;     if (!rg.primed) {
;         const int s1p = st == 2 ? 0 : st + 1;
;         BAR();
;         STAGE(st, 0);
;         STAGE(s1p, 1);
;         asm volatile("s_waitcnt vmcnt(6)" ::: "memory");
;         BAR();
;     }
;     if (grp == 1) BAR();
;     DI bool next(int& tm, int& tn) {
;         if (L >= end) return false;
;         const int gsz = 8 * ntn, grp = L / gsz, rem = L - grp * gsz, rows = min(8, ntm - grp * 8);
;         tn = rem / rows; tm = grp * 8 + (rem - tn * rows);
;         L += step; return true;
.Lgu_ranged:
	s_cmp_ge_u32 s51, s52
	s_cbranch_scc1 .LBB0_860
	v_and_b32_e32 v190, 63, v193
	v_and_b32_e32 v191, 15, v190
	v_lshrrev_b32_e32 v17, 4, v190
	v_lshrrev_b32_e32 v18, 3, v190
	v_and_b32_e32 v19, 7, v190
	v_xor_b32_e32 v195, v19, v17
	v_lshlrev_b32_e32 v195, 4, v195
	v_lshl_add_u32 v184, v18, 11, v195
	v_or_b32_e32 v195, 4, v17
	v_xor_b32_e32 v195, v19, v195
	v_lshlrev_b32_e32 v195, 4, v195
	v_add_u32_e32 v227, 8, v18
	v_lshl_add_u32 v185, v227, 11, v195
	v_lshrrev_b32_e32 v195, 1, v191
	v_xor_b32_e32 v195, v17, v195
	v_lshlrev_b32_e32 v195, 4, v195
	s_lshl_b32 s1, s33, 6
	v_add_u32_e32 v227, s1, v191
	v_lshl_add_u32 v186, v227, 7, v195
	v_xor_b32_e32 v187, 64, v186
	v_mul_u32_u24_e32 v228, 0x1600, v227
	s_lshl_b32 s1, s36, 5
	v_add_u32_e32 v227, s1, v191
	v_lshl_add_u32 v188, v227, 7, v195
	v_add_u32_e32 v188, 0x10000, v188
	v_xor_b32_e32 v189, 64, v188
	v_lshl_add_u32 v229, v17, 3, s1
	v_add_u32_e32 v237, v228, v229
	v_and_b32_e32 v227, 1, v17
	v_mul_u32_u24_e32 v227, 0x15ff8, v227
	v_add_u32_e32 v237, v237, v227
	s_mul_i32 s1, s51, 0x1745e
	s_lshr_b32 s2, s1, 24
	s_mul_i32 s1, s2, 0xb0
	s_sub_u32 s1, s51, s1
	s_lshr_b32 s3, s1, 3
	s_and_b32 s37, s1, 7
	s_cmp_lt_u32 s2, 8
	s_cselect_b32 s58, s3, s1
	s_cselect_b32 s37, s37, 0
	s_lshl_b32 s2, s2, 3
	s_add_i32 s57, s2, s37
	s_lshl_b32 s1, s57, 19
	s_lshl_b32 s2, s10, 15
	s_add_u32 s1, s1, s2
	s_add_u32 s1, s1, 0x3240000
	s_add_u32 s66, s88, s1
	s_addc_u32 s67, s89, 0
	s_add_u32 s68, s66, 0x40000
	s_addc_u32 s69, s67, 0
	s_lshl_b32 s1, s58, 19
	s_add_u32 s1, s1, s2
	s_add_u32 s1, s1, s61
	s_add_u32 s70, s88, s1
	s_addc_u32 s71, s89, 0
	s_add_u32 s72, s70, 0x40000
	s_addc_u32 s73, s71, 0
	s_add_i32 m0, s39, 0x10000
	s_nop 0
	global_load_lds_dwordx4 v184, s[70:71]
	s_add_i32 m0, s39, 0x10400
	s_nop 0
	global_load_lds_dwordx4 v185, s[70:71]
	s_add_u32 s70, s70, 0x80
	s_addc_u32 s71, s71, 0
	s_add_i32 m0, s39, 0x0
	s_nop 0
	global_load_lds_dwordx4 v184, s[66:67]
	s_add_i32 m0, s39, 0x400
	s_nop 0
	global_load_lds_dwordx4 v185, s[66:67]
	s_add_u32 s66, s66, 0x80
	s_addc_u32 s67, s67, 0
	s_add_i32 m0, s39, 0x14000
	s_nop 0
	global_load_lds_dwordx4 v184, s[72:73]
	s_add_i32 m0, s39, 0x14400
	s_nop 0
	global_load_lds_dwordx4 v185, s[72:73]
	s_add_u32 s72, s72, 0x80
	s_addc_u32 s73, s73, 0
	s_add_i32 m0, s39, 0x4000
	s_nop 0
	global_load_lds_dwordx4 v184, s[68:69]
	s_add_i32 m0, s39, 0x4400
	s_nop 0
	global_load_lds_dwordx4 v185, s[68:69]
	s_add_u32 s68, s68, 0x80
	s_addc_u32 s69, s69, 0
	s_add_i32 m0, s39, 0x18000
	s_nop 0
	global_load_lds_dwordx4 v184, s[70:71]
	s_add_i32 m0, s39, 0x18400
	s_nop 0
	global_load_lds_dwordx4 v185, s[70:71]
	s_add_u32 s70, s70, 0x80
	s_addc_u32 s71, s71, 0
	s_add_i32 m0, s39, 0x8000
	s_nop 0
	global_load_lds_dwordx4 v184, s[66:67]
	s_add_i32 m0, s39, 0x8400
	s_nop 0
	global_load_lds_dwordx4 v185, s[66:67]
	s_add_u32 s66, s66, 0x80
	s_addc_u32 s67, s67, 0
	s_add_i32 m0, s39, 0x1c000
	s_nop 0
	global_load_lds_dwordx4 v184, s[72:73]
	s_add_i32 m0, s39, 0x1c400
	s_nop 0
	global_load_lds_dwordx4 v185, s[72:73]
	s_add_u32 s72, s72, 0x80
	s_addc_u32 s73, s73, 0
	s_waitcnt vmcnt(8)
	s_barrier
	s_cmp_eq_u32 s33, 0
	s_cbranch_scc1 .Lgu_lead
	s_setprio 1
	s_barrier

; #define LAS __attribute__((address_space(3)))
; #define BAR() { __builtin_amdgcn_sched_barrier(0); __builtin_amdgcn_s_barrier(); asm volatile("" ::: "memory"); __builtin_amdgcn_sched_barrier(0); }
; DI void gemm_stream2(const bf16_t* __restrict__ A, int lda, const bf16_t* __restrict__ Bt, int ldb, int K, int m0, int n0, ...
;     ...
;     for (int kt = 0; kt < nk; ++kt) {
;         const bool pf = (kt + 2 < nk) || has_next, more = (kt + 1 < nk) || has_next;
;         const bf16_t* pa = (kt + 2 < nk) ? ga + (kt + 2) * 64 : gan + (kt + 2 - nk) * 64;
;         const bf16_t* pb = (kt + 2 < nk) ? gb + (kt + 2) * 64 : gbn + (kt + 2 - nk) * 64;
;         const int plda = (kt + 2 < nk) ? lda : ldan, pldb = (kt + 2 < nk) ? ldb : ldbn;
;         const int s2 = st >= 1 ? st - 1 : 2;
;         const LAS char* base = lds + st * 49152;
; #pragma unroll
;         for (int ks = 0; ks < 2; ++ks) {
;             const unsigned fo = ks ? fo1 : fo0;
;             bf16x8 af[4], bfr[4];
; #pragma unroll
;             for (int i = 0; i < 4; ++i) { af[i] = *(const LAS bf16x8*)(base + aoff + i * 2048 + fo); bfr[i] = *(const LAS bf16x8*)(base + boff + i * 2048 + fo); }
;             if (ks == 1 && more) { if (pf) asm volatile("s_waitcnt vmcnt(3)" ::: "memory"); else asm volatile("s_waitcnt vmcnt(0)" ::: "memory"); }
;             if (pf) { PIECE(s2, ks * 3 + 0); PIECE(s2, ks * 3 + 1); PIECE(s2, ks * 3 + 2); }
;             asm volatile("s_waitcnt lgkmcnt(0)" ::: "memory");
;             BAR();
;             __builtin_amdgcn_s_setprio(1);
; #pragma unroll
;             for (int mi = 0; mi < 4; ++mi)
; #pragma unroll
;                 for (int ni = 0; ni < 4; ++ni) acc[mi][ni] = __builtin_amdgcn_mfma_f32_16x16x32_bf16(bfr[ni], af[mi], acc[mi][ni], 0, 0, 0);
;             __builtin_amdgcn_s_setprio(0);
;             BAR();
;         }
.Lgu_kloop:
	ds_read_b128 v[0:3], v188 offset:16
	ds_read_b128 v[4:7], v189 offset:16
	ds_read_b128 v[8:11], v188 offset:2064
	ds_read_b128 v[12:15], v189 offset:2064
	ds_read_b128 v[196:199], v188 offset:16400
	ds_read_b128 v[200:203], v189 offset:16400
	ds_read_b128 v[204:207], v188 offset:18448
	ds_read_b128 v[208:211], v189 offset:18448
	ds_read_b128 v[152:155], v186 offset:16
	ds_read_b128 v[156:159], v187 offset:16
	ds_read_b128 v[160:163], v186 offset:2064
	ds_read_b128 v[164:167], v187 offset:2064
	ds_read_b128 v[168:171], v186 offset:4112
	ds_read_b128 v[172:175], v187 offset:4112
	ds_read_b128 v[176:179], v186 offset:6160
	ds_read_b128 v[180:183], v187 offset:6160
	s_add_i32 m0, s39, 0xc000
	s_nop 0
	global_load_lds_dwordx4 v184, s[68:69]
	s_add_i32 m0, s39, 0xc400
	s_nop 0
	global_load_lds_dwordx4 v185, s[68:69]
	s_add_u32 s68, s68, 0x80
	s_addc_u32 s69, s69, 0
	s_waitcnt lgkmcnt(0)
	s_waitcnt vmcnt(8)
	s_barrier
	v_mfma_f32_16x16x32_bf16 v[24:27], v[0:3], v[152:155], v[24:27]
	v_mfma_f32_16x16x32_bf16 v[28:31], v[8:11], v[152:155], v[28:31]
	v_mfma_f32_16x16x32_bf16 v[32:35], v[0:3], v[160:163], v[32:35]
	v_mfma_f32_16x16x32_bf16 v[36:39], v[8:11], v[160:163], v[36:39]
	v_mfma_f32_16x16x32_bf16 v[40:43], v[0:3], v[168:171], v[40:43]
	v_mfma_f32_16x16x32_bf16 v[44:47], v[8:11], v[168:171], v[44:47]
	v_mfma_f32_16x16x32_bf16 v[48:51], v[0:3], v[176:179], v[48:51]
	v_mfma_f32_16x16x32_bf16 v[52:55], v[8:11], v[176:179], v[52:55]
	v_mfma_f32_16x16x32_bf16 v[24:27], v[4:7], v[156:159], v[24:27]
	v_mfma_f32_16x16x32_bf16 v[28:31], v[12:15], v[156:159], v[28:31]
	v_mfma_f32_16x16x32_bf16 v[32:35], v[4:7], v[164:167], v[32:35]
	v_mfma_f32_16x16x32_bf16 v[36:39], v[12:15], v[164:167], v[36:39]
	v_mfma_f32_16x16x32_bf16 v[40:43], v[4:7], v[172:175], v[40:43]
	v_mfma_f32_16x16x32_bf16 v[44:47], v[12:15], v[172:175], v[44:47]
	v_mfma_f32_16x16x32_bf16 v[48:51], v[4:7], v[180:183], v[48:51]
	v_mfma_f32_16x16x32_bf16 v[52:55], v[12:15], v[180:183], v[52:55]
	v_mfma_f32_16x16x32_bf16 v[56:59], v[196:199], v[152:155], v[56:59]
	v_mfma_f32_16x16x32_bf16 v[60:63], v[204:207], v[152:155], v[60:63]
	v_mfma_f32_16x16x32_bf16 v[64:67], v[196:199], v[160:163], v[64:67]
	v_mfma_f32_16x16x32_bf16 v[68:71], v[204:207], v[160:163], v[68:71]
	v_mfma_f32_16x16x32_bf16 v[72:75], v[196:199], v[168:171], v[72:75]
	v_mfma_f32_16x16x32_bf16 v[76:79], v[204:207], v[168:171], v[76:79]
	v_mfma_f32_16x16x32_bf16 v[80:83], v[196:199], v[176:179], v[80:83]
	v_mfma_f32_16x16x32_bf16 v[84:87], v[204:207], v[176:179], v[84:87]
	v_mfma_f32_16x16x32_bf16 v[56:59], v[200:203], v[156:159], v[56:59]
	v_mfma_f32_16x16x32_bf16 v[60:63], v[208:211], v[156:159], v[60:63]
	v_mfma_f32_16x16x32_bf16 v[64:67], v[200:203], v[164:167], v[64:67]
	v_mfma_f32_16x16x32_bf16 v[68:71], v[208:211], v[164:167], v[68:71]
	v_mfma_f32_16x16x32_bf16 v[72:75], v[200:203], v[172:175], v[72:75]
	v_mfma_f32_16x16x32_bf16 v[76:79], v[208:211], v[172:175], v[76:79]
	v_mfma_f32_16x16x32_bf16 v[80:83], v[200:203], v[180:183], v[80:83]
	v_mfma_f32_16x16x32_bf16 v[84:87], v[208:211], v[180:183], v[84:87]
	s_barrier
	ds_read_b128 v[152:155], v186 offset:16400
	ds_read_b128 v[156:159], v187 offset:16400
	ds_read_b128 v[160:163], v186 offset:18448
	ds_read_b128 v[164:167], v187 offset:18448
	ds_read_b128 v[168:171], v186 offset:20496
	ds_read_b128 v[172:175], v187 offset:20496
	ds_read_b128 v[176:179], v186 offset:22544
	ds_read_b128 v[180:183], v187 offset:22544
	s_cmp_lg_u32 s0, s54
	s_cbranch_scc1 .Lgu_nosw1
	s_mov_b64 s[66:67], s[74:75]
	s_mov_b64 s[70:71], s[80:81]
	s_mov_b64 s[72:73], s[82:83]
.Lgu_nosw1:
	s_add_i32 m0, s39, 0x10000
	s_nop 0
	global_load_lds_dwordx4 v184, s[70:71]
	s_add_i32 m0, s39, 0x10400
	s_nop 0
	global_load_lds_dwordx4 v185, s[70:71]
	s_add_u32 s70, s70, 0x80
	s_addc_u32 s71, s71, 0
	s_add_i32 m0, s39, 0x0
	s_nop 0
	global_load_lds_dwordx4 v184, s[66:67]
	s_add_i32 m0, s39, 0x400
	s_nop 0
	global_load_lds_dwordx4 v185, s[66:67]
	s_add_u32 s66, s66, 0x80
	s_addc_u32 s67, s67, 0
	s_add_i32 m0, s39, 0x14000
	s_nop 0
	global_load_lds_dwordx4 v184, s[72:73]
	s_add_i32 m0, s39, 0x14400
	s_nop 0
	global_load_lds_dwordx4 v185, s[72:73]
	s_add_u32 s72, s72, 0x80
	s_addc_u32 s73, s73, 0
	s_waitcnt lgkmcnt(0)
	s_waitcnt vmcnt(8)
	s_barrier
	v_mfma_f32_16x16x32_bf16 v[88:91], v[0:3], v[152:155], v[88:91]
	v_mfma_f32_16x16x32_bf16 v[92:95], v[8:11], v[152:155], v[92:95]
	v_mfma_f32_16x16x32_bf16 v[96:99], v[0:3], v[160:163], v[96:99]
	v_mfma_f32_16x16x32_bf16 v[100:103], v[8:11], v[160:163], v[100:103]
	v_mfma_f32_16x16x32_bf16 v[104:107], v[0:3], v[168:171], v[104:107]
	v_mfma_f32_16x16x32_bf16 v[108:111], v[8:11], v[168:171], v[108:111]
	v_mfma_f32_16x16x32_bf16 v[112:115], v[0:3], v[176:179], v[112:115]
	v_mfma_f32_16x16x32_bf16 v[116:119], v[8:11], v[176:179], v[116:119]
	v_mfma_f32_16x16x32_bf16 v[88:91], v[4:7], v[156:159], v[88:91]
	v_mfma_f32_16x16x32_bf16 v[92:95], v[12:15], v[156:159], v[92:95]
	v_mfma_f32_16x16x32_bf16 v[96:99], v[4:7], v[164:167], v[96:99]
	v_mfma_f32_16x16x32_bf16 v[100:103], v[12:15], v[164:167], v[100:103]
	v_mfma_f32_16x16x32_bf16 v[104:107], v[4:7], v[172:175], v[104:107]
	v_mfma_f32_16x16x32_bf16 v[108:111], v[12:15], v[172:175], v[108:111]
	v_mfma_f32_16x16x32_bf16 v[112:115], v[4:7], v[180:183], v[112:115]
	v_mfma_f32_16x16x32_bf16 v[116:119], v[12:15], v[180:183], v[116:119]
	v_mfma_f32_16x16x32_bf16 v[120:123], v[196:199], v[152:155], v[120:123]
	v_mfma_f32_16x16x32_bf16 v[124:127], v[204:207], v[152:155], v[124:127]
	v_mfma_f32_16x16x32_bf16 v[128:131], v[196:199], v[160:163], v[128:131]
	v_mfma_f32_16x16x32_bf16 v[132:135], v[204:207], v[160:163], v[132:135]
	v_mfma_f32_16x16x32_bf16 v[136:139], v[196:199], v[168:171], v[136:139]
	v_mfma_f32_16x16x32_bf16 v[140:143], v[204:207], v[168:171], v[140:143]
	v_mfma_f32_16x16x32_bf16 v[144:147], v[196:199], v[176:179], v[144:147]
	v_mfma_f32_16x16x32_bf16 v[148:151], v[204:207], v[176:179], v[148:151]
	v_mfma_f32_16x16x32_bf16 v[120:123], v[200:203], v[156:159], v[120:123]
	v_mfma_f32_16x16x32_bf16 v[124:127], v[208:211], v[156:159], v[124:127]
	v_mfma_f32_16x16x32_bf16 v[128:131], v[200:203], v[164:167], v[128:131]
	v_mfma_f32_16x16x32_bf16 v[132:135], v[208:211], v[164:167], v[132:135]
	v_mfma_f32_16x16x32_bf16 v[136:139], v[200:203], v[172:175], v[136:139]
	v_mfma_f32_16x16x32_bf16 v[140:143], v[208:211], v[172:175], v[140:143]
	v_mfma_f32_16x16x32_bf16 v[144:147], v[200:203], v[180:183], v[144:147]
	v_mfma_f32_16x16x32_bf16 v[148:151], v[208:211], v[180:183], v[148:151]
	s_barrier
; #define LAS __attribute__((address_space(3)))
; #define BAR() { __builtin_amdgcn_sched_barrier(0); __builtin_amdgcn_s_barrier(); asm volatile("" ::: "memory"); __builtin_amdgcn_sched_barrier(0); }
; DI void gemm_stream2(const bf16_t* __restrict__ A, int lda, const bf16_t* __restrict__ Bt, int ldb, int K, int m0, int n0, ...
;     ...
;     for (int kt = 0; kt < nk; ++kt) {
;         const bool pf = (kt + 2 < nk) || has_next, more = (kt + 1 < nk) || has_next;
;         const bf16_t* pa = (kt + 2 < nk) ? ga + (kt + 2) * 64 : gan + (kt + 2 - nk) * 64;
;         const bf16_t* pb = (kt + 2 < nk) ? gb + (kt + 2) * 64 : gbn + (kt + 2 - nk) * 64;
;         const int plda = (kt + 2 < nk) ? lda : ldan, pldb = (kt + 2 < nk) ? ldb : ldbn;
;         const int s2 = st >= 1 ? st - 1 : 2;
;         const LAS char* base = lds + st * 49152;
; #pragma unroll
;         for (int ks = 0; ks < 2; ++ks) {
;             const unsigned fo = ks ? fo1 : fo0;
;             bf16x8 af[4], bfr[4];
; #pragma unroll
;             for (int i = 0; i < 4; ++i) { af[i] = *(const LAS bf16x8*)(base + aoff + i * 2048 + fo); bfr[i] = *(const LAS bf16x8*)(base + boff + i * 2048 + fo); }
;             if (ks == 1 && more) { if (pf) asm volatile("s_waitcnt vmcnt(3)" ::: "memory"); else asm volatile("s_waitcnt vmcnt(0)" ::: "memory"); }
;             if (pf) { PIECE(s2, ks * 3 + 0); PIECE(s2, ks * 3 + 1); PIECE(s2, ks * 3 + 2); }
;             asm volatile("s_waitcnt lgkmcnt(0)" ::: "memory");
;             BAR();
;             __builtin_amdgcn_s_setprio(1);
; #pragma unroll
;             for (int mi = 0; mi < 4; ++mi)
; #pragma unroll
;                 for (int ni = 0; ni < 4; ++ni) acc[mi][ni] = __builtin_amdgcn_mfma_f32_16x16x32_bf16(bfr[ni], af[mi], acc[mi][ni], 0, 0, 0);
;             __builtin_amdgcn_s_setprio(0);
;             BAR();
;         }
	ds_read_b128 v[0:3], v188 offset:32784
	ds_read_b128 v[4:7], v189 offset:32784
	ds_read_b128 v[8:11], v188 offset:34832
	ds_read_b128 v[12:15], v189 offset:34832
	ds_read_b128 v[196:199], v188 offset:49168
	ds_read_b128 v[200:203], v189 offset:49168
	ds_read_b128 v[204:207], v188 offset:51216
	ds_read_b128 v[208:211], v189 offset:51216
	ds_read_b128 v[152:155], v186 offset:32784
	ds_read_b128 v[156:159], v187 offset:32784
	ds_read_b128 v[160:163], v186 offset:34832
	ds_read_b128 v[164:167], v187 offset:34832
	ds_read_b128 v[168:171], v186 offset:36880
	ds_read_b128 v[172:175], v187 offset:36880
	ds_read_b128 v[176:179], v186 offset:38928
	ds_read_b128 v[180:183], v187 offset:38928
	s_cmp_lg_u32 s0, s54
	s_cbranch_scc1 .Lgu_nosw2
	s_mov_b64 s[68:69], s[78:79]
.Lgu_nosw2:
	s_add_i32 m0, s39, 0x4000
	s_nop 0
	global_load_lds_dwordx4 v184, s[68:69]
	s_add_i32 m0, s39, 0x4400
	s_nop 0
	global_load_lds_dwordx4 v185, s[68:69]
	s_add_u32 s68, s68, 0x80
	s_addc_u32 s69, s69, 0
	s_waitcnt lgkmcnt(0)
	s_waitcnt vmcnt(8)
	s_barrier
	v_mfma_f32_16x16x32_bf16 v[24:27], v[0:3], v[152:155], v[24:27]
	v_mfma_f32_16x16x32_bf16 v[28:31], v[8:11], v[152:155], v[28:31]
	v_mfma_f32_16x16x32_bf16 v[32:35], v[0:3], v[160:163], v[32:35]
	v_mfma_f32_16x16x32_bf16 v[36:39], v[8:11], v[160:163], v[36:39]
	v_mfma_f32_16x16x32_bf16 v[40:43], v[0:3], v[168:171], v[40:43]
	v_mfma_f32_16x16x32_bf16 v[44:47], v[8:11], v[168:171], v[44:47]
	v_mfma_f32_16x16x32_bf16 v[48:51], v[0:3], v[176:179], v[48:51]
	v_mfma_f32_16x16x32_bf16 v[52:55], v[8:11], v[176:179], v[52:55]
	v_mfma_f32_16x16x32_bf16 v[24:27], v[4:7], v[156:159], v[24:27]
	v_mfma_f32_16x16x32_bf16 v[28:31], v[12:15], v[156:159], v[28:31]
	v_mfma_f32_16x16x32_bf16 v[32:35], v[4:7], v[164:167], v[32:35]
	v_mfma_f32_16x16x32_bf16 v[36:39], v[12:15], v[164:167], v[36:39]
	v_mfma_f32_16x16x32_bf16 v[40:43], v[4:7], v[172:175], v[40:43]
	v_mfma_f32_16x16x32_bf16 v[44:47], v[12:15], v[172:175], v[44:47]
	v_mfma_f32_16x16x32_bf16 v[48:51], v[4:7], v[180:183], v[48:51]
	v_mfma_f32_16x16x32_bf16 v[52:55], v[12:15], v[180:183], v[52:55]
	v_mfma_f32_16x16x32_bf16 v[56:59], v[196:199], v[152:155], v[56:59]
	v_mfma_f32_16x16x32_bf16 v[60:63], v[204:207], v[152:155], v[60:63]
	v_mfma_f32_16x16x32_bf16 v[64:67], v[196:199], v[160:163], v[64:67]
	v_mfma_f32_16x16x32_bf16 v[68:71], v[204:207], v[160:163], v[68:71]
	v_mfma_f32_16x16x32_bf16 v[72:75], v[196:199], v[168:171], v[72:75]
	v_mfma_f32_16x16x32_bf16 v[76:79], v[204:207], v[168:171], v[76:79]
	v_mfma_f32_16x16x32_bf16 v[80:83], v[196:199], v[176:179], v[80:83]
	v_mfma_f32_16x16x32_bf16 v[84:87], v[204:207], v[176:179], v[84:87]
	v_mfma_f32_16x16x32_bf16 v[56:59], v[200:203], v[156:159], v[56:59]
	v_mfma_f32_16x16x32_bf16 v[60:63], v[208:211], v[156:159], v[60:63]
	v_mfma_f32_16x16x32_bf16 v[64:67], v[200:203], v[164:167], v[64:67]
	v_mfma_f32_16x16x32_bf16 v[68:71], v[208:211], v[164:167], v[68:71]
	v_mfma_f32_16x16x32_bf16 v[72:75], v[200:203], v[172:175], v[72:75]
	v_mfma_f32_16x16x32_bf16 v[76:79], v[208:211], v[172:175], v[76:79]
	v_mfma_f32_16x16x32_bf16 v[80:83], v[200:203], v[180:183], v[80:83]
	v_mfma_f32_16x16x32_bf16 v[84:87], v[208:211], v[180:183], v[84:87]
	s_barrier
	ds_read_b128 v[152:155], v186 offset:49168
	ds_read_b128 v[156:159], v187 offset:49168
	ds_read_b128 v[160:163], v186 offset:51216
	ds_read_b128 v[164:167], v187 offset:51216
	ds_read_b128 v[168:171], v186 offset:53264
	ds_read_b128 v[172:175], v187 offset:53264
	ds_read_b128 v[176:179], v186 offset:55312
	ds_read_b128 v[180:183], v187 offset:55312
	s_add_i32 m0, s39, 0x18000
	s_nop 0
	global_load_lds_dwordx4 v184, s[70:71]
	s_add_i32 m0, s39, 0x18400
	s_nop 0
	global_load_lds_dwordx4 v185, s[70:71]
	s_add_u32 s70, s70, 0x80
	s_addc_u32 s71, s71, 0
	s_add_i32 m0, s39, 0x8000
	s_nop 0
	global_load_lds_dwordx4 v184, s[66:67]
	s_add_i32 m0, s39, 0x8400
	s_nop 0
	global_load_lds_dwordx4 v185, s[66:67]
	s_add_u32 s66, s66, 0x80
	s_addc_u32 s67, s67, 0
	s_add_i32 m0, s39, 0x1c000
	s_nop 0
	global_load_lds_dwordx4 v184, s[72:73]
	s_add_i32 m0, s39, 0x1c400
	s_nop 0
	global_load_lds_dwordx4 v185, s[72:73]
	s_add_u32 s72, s72, 0x80
	s_addc_u32 s73, s73, 0
	s_waitcnt lgkmcnt(0)
	s_waitcnt vmcnt(8)
	s_barrier
	v_mfma_f32_16x16x32_bf16 v[88:91], v[0:3], v[152:155], v[88:91]
	v_mfma_f32_16x16x32_bf16 v[92:95], v[8:11], v[152:155], v[92:95]
	v_mfma_f32_16x16x32_bf16 v[96:99], v[0:3], v[160:163], v[96:99]
	v_mfma_f32_16x16x32_bf16 v[100:103], v[8:11], v[160:163], v[100:103]
	v_mfma_f32_16x16x32_bf16 v[104:107], v[0:3], v[168:171], v[104:107]
	v_mfma_f32_16x16x32_bf16 v[108:111], v[8:11], v[168:171], v[108:111]
	v_mfma_f32_16x16x32_bf16 v[112:115], v[0:3], v[176:179], v[112:115]
	v_mfma_f32_16x16x32_bf16 v[116:119], v[8:11], v[176:179], v[116:119]
	v_mfma_f32_16x16x32_bf16 v[88:91], v[4:7], v[156:159], v[88:91]
	v_mfma_f32_16x16x32_bf16 v[92:95], v[12:15], v[156:159], v[92:95]
	v_mfma_f32_16x16x32_bf16 v[96:99], v[4:7], v[164:167], v[96:99]
	v_mfma_f32_16x16x32_bf16 v[100:103], v[12:15], v[164:167], v[100:103]
	v_mfma_f32_16x16x32_bf16 v[104:107], v[4:7], v[172:175], v[104:107]
	v_mfma_f32_16x16x32_bf16 v[108:111], v[12:15], v[172:175], v[108:111]
	v_mfma_f32_16x16x32_bf16 v[112:115], v[4:7], v[180:183], v[112:115]
	v_mfma_f32_16x16x32_bf16 v[116:119], v[12:15], v[180:183], v[116:119]
	v_mfma_f32_16x16x32_bf16 v[120:123], v[196:199], v[152:155], v[120:123]
	v_mfma_f32_16x16x32_bf16 v[124:127], v[204:207], v[152:155], v[124:127]
	v_mfma_f32_16x16x32_bf16 v[128:131], v[196:199], v[160:163], v[128:131]
	v_mfma_f32_16x16x32_bf16 v[132:135], v[204:207], v[160:163], v[132:135]
	v_mfma_f32_16x16x32_bf16 v[136:139], v[196:199], v[168:171], v[136:139]
	v_mfma_f32_16x16x32_bf16 v[140:143], v[204:207], v[168:171], v[140:143]
	v_mfma_f32_16x16x32_bf16 v[144:147], v[196:199], v[176:179], v[144:147]
	v_mfma_f32_16x16x32_bf16 v[148:151], v[204:207], v[176:179], v[148:151]
	v_mfma_f32_16x16x32_bf16 v[120:123], v[200:203], v[156:159], v[120:123]
	v_mfma_f32_16x16x32_bf16 v[124:127], v[208:211], v[156:159], v[124:127]
	v_mfma_f32_16x16x32_bf16 v[128:131], v[200:203], v[164:167], v[128:131]
	v_mfma_f32_16x16x32_bf16 v[132:135], v[208:211], v[164:167], v[132:135]
	v_mfma_f32_16x16x32_bf16 v[136:139], v[200:203], v[172:175], v[136:139]
	v_mfma_f32_16x16x32_bf16 v[140:143], v[208:211], v[172:175], v[140:143]
	v_mfma_f32_16x16x32_bf16 v[144:147], v[200:203], v[180:183], v[144:147]
	v_mfma_f32_16x16x32_bf16 v[148:151], v[208:211], v[180:183], v[148:151]
	s_barrier
; #define LAS __attribute__((address_space(3)))
; #define BAR() { __builtin_amdgcn_sched_barrier(0); __builtin_amdgcn_s_barrier(); asm volatile("" ::: "memory"); __builtin_amdgcn_sched_barrier(0); }
; DI void gemm_stream2(const bf16_t* __restrict__ A, int lda, const bf16_t* __restrict__ Bt, int ldb, int K, int m0, int n0, ...
;     ...
;     for (int kt = 0; kt < nk; ++kt) {
;         const bool pf = (kt + 2 < nk) || has_next, more = (kt + 1 < nk) || has_next;
;         const bf16_t* pa = (kt + 2 < nk) ? ga + (kt + 2) * 64 : gan + (kt + 2 - nk) * 64;
;         const bf16_t* pb = (kt + 2 < nk) ? gb + (kt + 2) * 64 : gbn + (kt + 2 - nk) * 64;
;         const int plda = (kt + 2 < nk) ? lda : ldan, pldb = (kt + 2 < nk) ? ldb : ldbn;
;         const int s2 = st >= 1 ? st - 1 : 2;
;         const LAS char* base = lds + st * 49152;
; #pragma unroll
;         for (int ks = 0; ks < 2; ++ks) {
;             const unsigned fo = ks ? fo1 : fo0;
;             bf16x8 af[4], bfr[4];
; #pragma unroll
;             for (int i = 0; i < 4; ++i) { af[i] = *(const LAS bf16x8*)(base + aoff + i * 2048 + fo); bfr[i] = *(const LAS bf16x8*)(base + boff + i * 2048 + fo); }
;             if (ks == 1 && more) { if (pf) asm volatile("s_waitcnt vmcnt(3)" ::: "memory"); else asm volatile("s_waitcnt vmcnt(0)" ::: "memory"); }
;             if (pf) { PIECE(s2, ks * 3 + 0); PIECE(s2, ks * 3 + 1); PIECE(s2, ks * 3 + 2); }
;             asm volatile("s_waitcnt lgkmcnt(0)" ::: "memory");
;             BAR();
;             __builtin_amdgcn_s_setprio(1);
; #pragma unroll
;             for (int mi = 0; mi < 4; ++mi)
; #pragma unroll
;                 for (int ni = 0; ni < 4; ++ni) acc[mi][ni] = __builtin_amdgcn_mfma_f32_16x16x32_bf16(bfr[ni], af[mi], acc[mi][ni], 0, 0, 0);
;             __builtin_amdgcn_s_setprio(0);
;             BAR();
;         }
;         st = st == 2 ? 0 : st + 1;
;     }
;     if (grp == 0) BAR();
	s_sub_u32 s0, s0, 1
	s_cmp_lg_u32 s0, 0
	s_cbranch_scc1 .Lgu_kloop
	s_cmp_lg_u32 s54, 0
	s_cbranch_scc1 .Lgu_epi
	ds_read_b128 v[0:3], v188 offset:16
	ds_read_b128 v[4:7], v189 offset:16
	ds_read_b128 v[8:11], v188 offset:2064
	ds_read_b128 v[12:15], v189 offset:2064
	ds_read_b128 v[196:199], v188 offset:16400
	ds_read_b128 v[200:203], v189 offset:16400
	ds_read_b128 v[204:207], v188 offset:18448
	ds_read_b128 v[208:211], v189 offset:18448
	ds_read_b128 v[152:155], v186 offset:16
	ds_read_b128 v[156:159], v187 offset:16
	ds_read_b128 v[160:163], v186 offset:2064
	ds_read_b128 v[164:167], v187 offset:2064
	ds_read_b128 v[168:171], v186 offset:4112
	ds_read_b128 v[172:175], v187 offset:4112
	ds_read_b128 v[176:179], v186 offset:6160
	ds_read_b128 v[180:183], v187 offset:6160
	s_add_i32 m0, s39, 0xc000
	s_nop 0
	global_load_lds_dwordx4 v184, s[68:69]
	s_add_i32 m0, s39, 0xc400
	s_nop 0
	global_load_lds_dwordx4 v185, s[68:69]
	s_add_u32 s68, s68, 0x80
	s_addc_u32 s69, s69, 0
	s_waitcnt lgkmcnt(0)
	s_waitcnt vmcnt(8)
	s_barrier
	v_mfma_f32_16x16x32_bf16 v[24:27], v[0:3], v[152:155], v[24:27]
	v_mfma_f32_16x16x32_bf16 v[28:31], v[8:11], v[152:155], v[28:31]
	v_mfma_f32_16x16x32_bf16 v[32:35], v[0:3], v[160:163], v[32:35]
	v_mfma_f32_16x16x32_bf16 v[36:39], v[8:11], v[160:163], v[36:39]
	v_mfma_f32_16x16x32_bf16 v[40:43], v[0:3], v[168:171], v[40:43]
	v_mfma_f32_16x16x32_bf16 v[44:47], v[8:11], v[168:171], v[44:47]
	v_mfma_f32_16x16x32_bf16 v[48:51], v[0:3], v[176:179], v[48:51]
	v_mfma_f32_16x16x32_bf16 v[52:55], v[8:11], v[176:179], v[52:55]
	v_mfma_f32_16x16x32_bf16 v[24:27], v[4:7], v[156:159], v[24:27]
	v_mfma_f32_16x16x32_bf16 v[28:31], v[12:15], v[156:159], v[28:31]
	v_mfma_f32_16x16x32_bf16 v[32:35], v[4:7], v[164:167], v[32:35]
	v_mfma_f32_16x16x32_bf16 v[36:39], v[12:15], v[164:167], v[36:39]
	v_mfma_f32_16x16x32_bf16 v[40:43], v[4:7], v[172:175], v[40:43]
	v_mfma_f32_16x16x32_bf16 v[44:47], v[12:15], v[172:175], v[44:47]
	v_mfma_f32_16x16x32_bf16 v[48:51], v[4:7], v[180:183], v[48:51]
	v_mfma_f32_16x16x32_bf16 v[52:55], v[12:15], v[180:183], v[52:55]
	v_mfma_f32_16x16x32_bf16 v[56:59], v[196:199], v[152:155], v[56:59]
	v_mfma_f32_16x16x32_bf16 v[60:63], v[204:207], v[152:155], v[60:63]
	v_mfma_f32_16x16x32_bf16 v[64:67], v[196:199], v[160:163], v[64:67]
	v_mfma_f32_16x16x32_bf16 v[68:71], v[204:207], v[160:163], v[68:71]
	v_mfma_f32_16x16x32_bf16 v[72:75], v[196:199], v[168:171], v[72:75]
	v_mfma_f32_16x16x32_bf16 v[76:79], v[204:207], v[168:171], v[76:79]
	v_mfma_f32_16x16x32_bf16 v[80:83], v[196:199], v[176:179], v[80:83]
	v_mfma_f32_16x16x32_bf16 v[84:87], v[204:207], v[176:179], v[84:87]
	v_mfma_f32_16x16x32_bf16 v[56:59], v[200:203], v[156:159], v[56:59]
	v_mfma_f32_16x16x32_bf16 v[60:63], v[208:211], v[156:159], v[60:63]
	v_mfma_f32_16x16x32_bf16 v[64:67], v[200:203], v[164:167], v[64:67]
	v_mfma_f32_16x16x32_bf16 v[68:71], v[208:211], v[164:167], v[68:71]
	v_mfma_f32_16x16x32_bf16 v[72:75], v[200:203], v[172:175], v[72:75]
	v_mfma_f32_16x16x32_bf16 v[76:79], v[208:211], v[172:175], v[76:79]
	v_mfma_f32_16x16x32_bf16 v[80:83], v[200:203], v[180:183], v[80:83]
	v_mfma_f32_16x16x32_bf16 v[84:87], v[208:211], v[180:183], v[84:87]
	s_barrier
	ds_read_b128 v[152:155], v186 offset:16400
	ds_read_b128 v[156:159], v187 offset:16400
	ds_read_b128 v[160:163], v186 offset:18448
	ds_read_b128 v[164:167], v187 offset:18448
	ds_read_b128 v[168:171], v186 offset:20496
	ds_read_b128 v[172:175], v187 offset:20496
	ds_read_b128 v[176:179], v186 offset:22544
	ds_read_b128 v[180:183], v187 offset:22544
	s_waitcnt lgkmcnt(0)
	s_waitcnt vmcnt(2)
	s_barrier
	v_mfma_f32_16x16x32_bf16 v[88:91], v[0:3], v[152:155], v[88:91]
	v_mfma_f32_16x16x32_bf16 v[92:95], v[8:11], v[152:155], v[92:95]
	v_mfma_f32_16x16x32_bf16 v[96:99], v[0:3], v[160:163], v[96:99]
	v_mfma_f32_16x16x32_bf16 v[100:103], v[8:11], v[160:163], v[100:103]
	v_mfma_f32_16x16x32_bf16 v[104:107], v[0:3], v[168:171], v[104:107]
	v_mfma_f32_16x16x32_bf16 v[108:111], v[8:11], v[168:171], v[108:111]
	v_mfma_f32_16x16x32_bf16 v[112:115], v[0:3], v[176:179], v[112:115]
	v_mfma_f32_16x16x32_bf16 v[116:119], v[8:11], v[176:179], v[116:119]
	v_mfma_f32_16x16x32_bf16 v[88:91], v[4:7], v[156:159], v[88:91]
	v_mfma_f32_16x16x32_bf16 v[92:95], v[12:15], v[156:159], v[92:95]
	v_mfma_f32_16x16x32_bf16 v[96:99], v[4:7], v[164:167], v[96:99]
	v_mfma_f32_16x16x32_bf16 v[100:103], v[12:15], v[164:167], v[100:103]
	v_mfma_f32_16x16x32_bf16 v[104:107], v[4:7], v[172:175], v[104:107]
	v_mfma_f32_16x16x32_bf16 v[108:111], v[12:15], v[172:175], v[108:111]
	v_mfma_f32_16x16x32_bf16 v[112:115], v[4:7], v[180:183], v[112:115]
	v_mfma_f32_16x16x32_bf16 v[116:119], v[12:15], v[180:183], v[116:119]
	v_mfma_f32_16x16x32_bf16 v[120:123], v[196:199], v[152:155], v[120:123]
	v_mfma_f32_16x16x32_bf16 v[124:127], v[204:207], v[152:155], v[124:127]
	v_mfma_f32_16x16x32_bf16 v[128:131], v[196:199], v[160:163], v[128:131]
	v_mfma_f32_16x16x32_bf16 v[132:135], v[204:207], v[160:163], v[132:135]
	v_mfma_f32_16x16x32_bf16 v[136:139], v[196:199], v[168:171], v[136:139]
	v_mfma_f32_16x16x32_bf16 v[140:143], v[204:207], v[168:171], v[140:143]
	v_mfma_f32_16x16x32_bf16 v[144:147], v[196:199], v[176:179], v[144:147]
	v_mfma_f32_16x16x32_bf16 v[148:151], v[204:207], v[176:179], v[148:151]
	v_mfma_f32_16x16x32_bf16 v[120:123], v[200:203], v[156:159], v[120:123]
	v_mfma_f32_16x16x32_bf16 v[124:127], v[208:211], v[156:159], v[124:127]
	v_mfma_f32_16x16x32_bf16 v[128:131], v[200:203], v[164:167], v[128:131]
	v_mfma_f32_16x16x32_bf16 v[132:135], v[208:211], v[164:167], v[132:135]
	v_mfma_f32_16x16x32_bf16 v[136:139], v[200:203], v[172:175], v[136:139]
	v_mfma_f32_16x16x32_bf16 v[140:143], v[208:211], v[172:175], v[140:143]
	v_mfma_f32_16x16x32_bf16 v[144:147], v[200:203], v[180:183], v[144:147]
	v_mfma_f32_16x16x32_bf16 v[148:151], v[208:211], v[180:183], v[148:151]
	s_barrier
; #define LAS __attribute__((address_space(3)))
; #define BAR() { __builtin_amdgcn_sched_barrier(0); __builtin_amdgcn_s_barrier(); asm volatile("" ::: "memory"); __builtin_amdgcn_sched_barrier(0); }
; DI void gemm_stream2(const bf16_t* __restrict__ A, int lda, const bf16_t* __restrict__ Bt, int ldb, int K, int m0, int n0, ...
;     ...
;         const int s2 = st >= 1 ? st - 1 : 2;
;         const LAS char* base = lds + st * 49152;
; #pragma unroll
;         for (int ks = 0; ks < 2; ++ks) {
;             const unsigned fo = ks ? fo1 : fo0;
;             bf16x8 af[4], bfr[4];
; #pragma unroll
;             for (int i = 0; i < 4; ++i) { af[i] = *(const LAS bf16x8*)(base + aoff + i * 2048 + fo); bfr[i] = *(const LAS bf16x8*)(base + boff + i * 2048 + fo); }
;             if (ks == 1 && more) { if (pf) asm volatile("s_waitcnt vmcnt(3)" ::: "memory"); else asm volatile("s_waitcnt vmcnt(0)" ::: "memory"); }
;             if (pf) { PIECE(s2, ks * 3 + 0); PIECE(s2, ks * 3 + 1); PIECE(s2, ks * 3 + 2); }
;             asm volatile("s_waitcnt lgkmcnt(0)" ::: "memory");
;             BAR();
;             __builtin_amdgcn_s_setprio(1);
; #pragma unroll
;             for (int mi = 0; mi < 4; ++mi)
; #pragma unroll
;                 for (int ni = 0; ni < 4; ++ni) acc[mi][ni] = __builtin_amdgcn_mfma_f32_16x16x32_bf16(bfr[ni], af[mi], acc[mi][ni], 0, 0, 0);
;             __builtin_amdgcn_s_setprio(0);
;             BAR();
;         }
;         st = st == 2 ? 0 : st + 1;
;     }
;     if (grp == 0) BAR();
	ds_read_b128 v[0:3], v188 offset:32784
	ds_read_b128 v[4:7], v189 offset:32784
	ds_read_b128 v[8:11], v188 offset:34832
	ds_read_b128 v[12:15], v189 offset:34832
	ds_read_b128 v[196:199], v188 offset:49168
	ds_read_b128 v[200:203], v189 offset:49168
	ds_read_b128 v[204:207], v188 offset:51216
	ds_read_b128 v[208:211], v189 offset:51216
	ds_read_b128 v[152:155], v186 offset:32784
	ds_read_b128 v[156:159], v187 offset:32784
	ds_read_b128 v[160:163], v186 offset:34832
	ds_read_b128 v[164:167], v187 offset:34832
	ds_read_b128 v[168:171], v186 offset:36880
	ds_read_b128 v[172:175], v187 offset:36880
	ds_read_b128 v[176:179], v186 offset:38928
	ds_read_b128 v[180:183], v187 offset:38928
	s_waitcnt lgkmcnt(0)
	s_waitcnt vmcnt(0)
	s_barrier
	v_mfma_f32_16x16x32_bf16 v[24:27], v[0:3], v[152:155], v[24:27]
	v_mfma_f32_16x16x32_bf16 v[28:31], v[8:11], v[152:155], v[28:31]
	v_mfma_f32_16x16x32_bf16 v[32:35], v[0:3], v[160:163], v[32:35]
	v_mfma_f32_16x16x32_bf16 v[36:39], v[8:11], v[160:163], v[36:39]
	v_mfma_f32_16x16x32_bf16 v[40:43], v[0:3], v[168:171], v[40:43]
	v_mfma_f32_16x16x32_bf16 v[44:47], v[8:11], v[168:171], v[44:47]
	v_mfma_f32_16x16x32_bf16 v[48:51], v[0:3], v[176:179], v[48:51]
	v_mfma_f32_16x16x32_bf16 v[52:55], v[8:11], v[176:179], v[52:55]
	v_mfma_f32_16x16x32_bf16 v[24:27], v[4:7], v[156:159], v[24:27]
	v_mfma_f32_16x16x32_bf16 v[28:31], v[12:15], v[156:159], v[28:31]
	v_mfma_f32_16x16x32_bf16 v[32:35], v[4:7], v[164:167], v[32:35]
	v_mfma_f32_16x16x32_bf16 v[36:39], v[12:15], v[164:167], v[36:39]
	v_mfma_f32_16x16x32_bf16 v[40:43], v[4:7], v[172:175], v[40:43]
	v_mfma_f32_16x16x32_bf16 v[44:47], v[12:15], v[172:175], v[44:47]
	v_mfma_f32_16x16x32_bf16 v[48:51], v[4:7], v[180:183], v[48:51]
	v_mfma_f32_16x16x32_bf16 v[52:55], v[12:15], v[180:183], v[52:55]
	v_mfma_f32_16x16x32_bf16 v[56:59], v[196:199], v[152:155], v[56:59]
	v_mfma_f32_16x16x32_bf16 v[60:63], v[204:207], v[152:155], v[60:63]
	v_mfma_f32_16x16x32_bf16 v[64:67], v[196:199], v[160:163], v[64:67]
	v_mfma_f32_16x16x32_bf16 v[68:71], v[204:207], v[160:163], v[68:71]
	v_mfma_f32_16x16x32_bf16 v[72:75], v[196:199], v[168:171], v[72:75]
	v_mfma_f32_16x16x32_bf16 v[76:79], v[204:207], v[168:171], v[76:79]
	v_mfma_f32_16x16x32_bf16 v[80:83], v[196:199], v[176:179], v[80:83]
	v_mfma_f32_16x16x32_bf16 v[84:87], v[204:207], v[176:179], v[84:87]
	v_mfma_f32_16x16x32_bf16 v[56:59], v[200:203], v[156:159], v[56:59]
	v_mfma_f32_16x16x32_bf16 v[60:63], v[208:211], v[156:159], v[60:63]
	v_mfma_f32_16x16x32_bf16 v[64:67], v[200:203], v[164:167], v[64:67]
	v_mfma_f32_16x16x32_bf16 v[68:71], v[208:211], v[164:167], v[68:71]
	v_mfma_f32_16x16x32_bf16 v[72:75], v[200:203], v[172:175], v[72:75]
	v_mfma_f32_16x16x32_bf16 v[76:79], v[208:211], v[172:175], v[76:79]
	v_mfma_f32_16x16x32_bf16 v[80:83], v[200:203], v[180:183], v[80:83]
	v_mfma_f32_16x16x32_bf16 v[84:87], v[208:211], v[180:183], v[84:87]
	s_barrier
	ds_read_b128 v[152:155], v186 offset:49168
	ds_read_b128 v[156:159], v187 offset:49168
	ds_read_b128 v[160:163], v186 offset:51216
	ds_read_b128 v[164:167], v187 offset:51216
	ds_read_b128 v[168:171], v186 offset:53264
	ds_read_b128 v[172:175], v187 offset:53264
	ds_read_b128 v[176:179], v186 offset:55312
	ds_read_b128 v[180:183], v187 offset:55312
	s_waitcnt lgkmcnt(0)
	s_barrier
	v_mfma_f32_16x16x32_bf16 v[88:91], v[0:3], v[152:155], v[88:91]
	v_mfma_f32_16x16x32_bf16 v[92:95], v[8:11], v[152:155], v[92:95]
	v_mfma_f32_16x16x32_bf16 v[96:99], v[0:3], v[160:163], v[96:99]
	v_mfma_f32_16x16x32_bf16 v[100:103], v[8:11], v[160:163], v[100:103]
	v_mfma_f32_16x16x32_bf16 v[104:107], v[0:3], v[168:171], v[104:107]
	v_mfma_f32_16x16x32_bf16 v[108:111], v[8:11], v[168:171], v[108:111]
	v_mfma_f32_16x16x32_bf16 v[112:115], v[0:3], v[176:179], v[112:115]
	v_mfma_f32_16x16x32_bf16 v[116:119], v[8:11], v[176:179], v[116:119]
	v_mfma_f32_16x16x32_bf16 v[88:91], v[4:7], v[156:159], v[88:91]
	v_mfma_f32_16x16x32_bf16 v[92:95], v[12:15], v[156:159], v[92:95]
	v_mfma_f32_16x16x32_bf16 v[96:99], v[4:7], v[164:167], v[96:99]
	v_mfma_f32_16x16x32_bf16 v[100:103], v[12:15], v[164:167], v[100:103]
	v_mfma_f32_16x16x32_bf16 v[104:107], v[4:7], v[172:175], v[104:107]
	v_mfma_f32_16x16x32_bf16 v[108:111], v[12:15], v[172:175], v[108:111]
	v_mfma_f32_16x16x32_bf16 v[112:115], v[4:7], v[180:183], v[112:115]
	v_mfma_f32_16x16x32_bf16 v[116:119], v[12:15], v[180:183], v[116:119]
	v_mfma_f32_16x16x32_bf16 v[120:123], v[196:199], v[152:155], v[120:123]
	v_mfma_f32_16x16x32_bf16 v[124:127], v[204:207], v[152:155], v[124:127]
	v_mfma_f32_16x16x32_bf16 v[128:131], v[196:199], v[160:163], v[128:131]
	v_mfma_f32_16x16x32_bf16 v[132:135], v[204:207], v[160:163], v[132:135]
	v_mfma_f32_16x16x32_bf16 v[136:139], v[196:199], v[168:171], v[136:139]
	v_mfma_f32_16x16x32_bf16 v[140:143], v[204:207], v[168:171], v[140:143]
	v_mfma_f32_16x16x32_bf16 v[144:147], v[196:199], v[176:179], v[144:147]
	v_mfma_f32_16x16x32_bf16 v[148:151], v[204:207], v[176:179], v[148:151]
	v_mfma_f32_16x16x32_bf16 v[120:123], v[200:203], v[156:159], v[120:123]
	v_mfma_f32_16x16x32_bf16 v[124:127], v[208:211], v[156:159], v[124:127]
	v_mfma_f32_16x16x32_bf16 v[128:131], v[200:203], v[164:167], v[128:131]
	v_mfma_f32_16x16x32_bf16 v[132:135], v[208:211], v[164:167], v[132:135]
	v_mfma_f32_16x16x32_bf16 v[136:139], v[200:203], v[172:175], v[136:139]
	v_mfma_f32_16x16x32_bf16 v[140:143], v[208:211], v[172:175], v[140:143]
	v_mfma_f32_16x16x32_bf16 v[144:147], v[200:203], v[180:183], v[144:147]
	v_mfma_f32_16x16x32_bf16 v[148:151], v[208:211], v[180:183], v[148:151]
	s_barrier
	s_cmp_lg_u32 s33, 0
	s_cbranch_scc1 .Lgu_epi
	s_barrier

; extern "C" __global__ void __launch_bounds__(512, 2) fwd_kernel(Params p, int ph0, int ph1) {
;     ...
;     for (int ph = ph0; ph < ph1; ++ph) {
;         run_phase(p, ph, blockIdx.x, gridDim.x, smem);
;         if (ph + 1 < ph1) xcd_barrier(xb);
;     }
.LBB0_860:
	s_setprio 0
	s_add_i32 s46, s46, 1
	s_cmp_ge_i32 s46, s47
	s_mov_b64 s[0:1], -1
	v_readlane_b32 s80, v238, 62
	v_readlane_b32 s81, v238, 63
	s_cbranch_scc0 .LBB0_861
	s_getpc_b64 s[98:99]
